# FFN-in bias rows computed per layer by the non-latent WGs in their scan-phase tail (pre phase keeps the in-projection bias rows only)
# speedup vs baseline: 1.0215x; 1.0215x over previous
.Ltr_done:
	s_waitcnt vmcnt(0)
	s_cmp_eq_u32 s61, 0
	s_cbranch_scc0 .Ltr_ret_prep
	s_load_dwordx2 s[56:57], s[100:101], 0x110
	s_load_dwordx2 s[84:85], s[100:101], 0x1b0
	s_load_dwordx2 s[72:73], s[100:101], 0x218
	v_readlane_b32 s59, v227, 0
	v_readfirstlane_b32 s60, v131
	s_nop 0
	s_add_i32 s59, s59, 0xffffff80
	s_lshl_b32 s59, s59, 2
	s_lshr_b32 s60, s60, 6
	s_add_i32 s59, s59, s60
	s_movk_i32 s60, 0x1600
	v_and_b32_e32 v2, 63, v131
	v_lshlrev_b32_e32 v3, 6, v2
	v_lshlrev_b32_e32 v2, 5, v2
	v_add_u32_e32 v4, 0x6000, v3
	v_add_u32_e32 v5, 0xc000, v3
	v_add_u32_e32 v6, 0x12000, v3
	v_add_u32_e32 v7, 0x18000, v3
	s_waitcnt lgkmcnt(0)
	s_mul_i32 s20, s58, 0xb00000
	s_add_u32 s56, s56, s20
	s_addc_u32 s57, s57, 0
	s_mul_i32 s20, s58, 0x1e000
	s_add_u32 s84, s84, s20
	s_addc_u32 s85, s85, 0
	s_mul_i32 s20, s58, 0x1b800
	s_add_u32 s72, s72, s20
	s_addc_u32 s73, s73, 0
	s_add_u32 s84, s84, 0x3000
	s_addc_u32 s85, s85, 0
.Lb_loop:
	s_cmp_ge_u32 s59, s60
	s_cbranch_scc1 .Ltr_ret_scan
	s_lshl_b32 s66, s59, 11
	s_add_u32 s2, s56, s66
	s_addc_u32 s3, s57, 0
	s_lshl_b32 s66, s59, 2
	s_add_u32 s64, s72, s66
	s_addc_u32 s65, s73, 0
	global_load_dwordx4 v[10:13], v2, s[2:3]
	global_load_dwordx4 v[14:17], v2, s[2:3] offset:16
	global_load_dwordx4 v[40:43], v3, s[84:85] offset:0
	global_load_dwordx4 v[44:47], v3, s[84:85] offset:16
	global_load_dwordx4 v[48:51], v3, s[84:85] offset:32
	global_load_dwordx4 v[52:55], v3, s[84:85] offset:48
	global_load_dwordx4 v[56:59], v4, s[84:85] offset:0
	global_load_dwordx4 v[60:63], v4, s[84:85] offset:16
	global_load_dwordx4 v[64:67], v4, s[84:85] offset:32
	global_load_dwordx4 v[68:71], v4, s[84:85] offset:48
	global_load_dwordx4 v[72:75], v5, s[84:85] offset:0
	global_load_dwordx4 v[76:79], v5, s[84:85] offset:16
	global_load_dwordx4 v[80:83], v5, s[84:85] offset:32
	global_load_dwordx4 v[84:87], v5, s[84:85] offset:48
	global_load_dwordx4 v[88:91], v6, s[84:85] offset:0
	global_load_dwordx4 v[92:95], v6, s[84:85] offset:16
	global_load_dwordx4 v[96:99], v6, s[84:85] offset:32
	global_load_dwordx4 v[100:103], v6, s[84:85] offset:48
	global_load_dwordx4 v[104:107], v7, s[84:85] offset:0
	global_load_dwordx4 v[108:111], v7, s[84:85] offset:16
	global_load_dwordx4 v[112:115], v7, s[84:85] offset:32
	global_load_dwordx4 v[116:119], v7, s[84:85] offset:48
	s_waitcnt vmcnt(0)
	v_lshrrev_b32_e32 v18, 16, v10
	v_cvt_f32_f16_e32 v20, v10
	v_cvt_f32_f16_e32 v21, v18
	v_lshrrev_b32_e32 v18, 16, v11
	v_cvt_f32_f16_e32 v22, v11
	v_cvt_f32_f16_e32 v23, v18
	v_lshrrev_b32_e32 v18, 16, v12
	v_cvt_f32_f16_e32 v24, v12
	v_cvt_f32_f16_e32 v25, v18
	v_lshrrev_b32_e32 v18, 16, v13
	v_cvt_f32_f16_e32 v26, v13
	v_cvt_f32_f16_e32 v27, v18
	v_lshrrev_b32_e32 v18, 16, v14
	v_cvt_f32_f16_e32 v28, v14
	v_cvt_f32_f16_e32 v29, v18
	v_lshrrev_b32_e32 v18, 16, v15
	v_cvt_f32_f16_e32 v30, v15
	v_cvt_f32_f16_e32 v31, v18
	v_lshrrev_b32_e32 v18, 16, v16
	v_cvt_f32_f16_e32 v32, v16
	v_cvt_f32_f16_e32 v33, v18
	v_lshrrev_b32_e32 v18, 16, v17
	v_cvt_f32_f16_e32 v34, v17
	v_cvt_f32_f16_e32 v35, v18
	v_mul_f32_e32 v120, v40, v20
	v_fmac_f32_e32 v120, v41, v21
	v_fmac_f32_e32 v120, v42, v22
	v_fmac_f32_e32 v120, v43, v23
	v_fmac_f32_e32 v120, v44, v24
	v_fmac_f32_e32 v120, v45, v25
	v_fmac_f32_e32 v120, v46, v26
	v_fmac_f32_e32 v120, v47, v27
	v_fmac_f32_e32 v120, v48, v28
	v_fmac_f32_e32 v120, v49, v29
	v_fmac_f32_e32 v120, v50, v30
	v_fmac_f32_e32 v120, v51, v31
	v_fmac_f32_e32 v120, v52, v32
	v_fmac_f32_e32 v120, v53, v33
	v_fmac_f32_e32 v120, v54, v34
	v_fmac_f32_e32 v120, v55, v35
	v_mul_f32_e32 v121, v56, v20
	v_fmac_f32_e32 v121, v57, v21
	v_fmac_f32_e32 v121, v58, v22
	v_fmac_f32_e32 v121, v59, v23
	v_fmac_f32_e32 v121, v60, v24
	v_fmac_f32_e32 v121, v61, v25
	v_fmac_f32_e32 v121, v62, v26
	v_fmac_f32_e32 v121, v63, v27
	v_fmac_f32_e32 v121, v64, v28
	v_fmac_f32_e32 v121, v65, v29
	v_fmac_f32_e32 v121, v66, v30
	v_fmac_f32_e32 v121, v67, v31
	v_fmac_f32_e32 v121, v68, v32
	v_fmac_f32_e32 v121, v69, v33
	v_fmac_f32_e32 v121, v70, v34
	v_fmac_f32_e32 v121, v71, v35
	v_mul_f32_e32 v122, v72, v20
	v_fmac_f32_e32 v122, v73, v21
	v_fmac_f32_e32 v122, v74, v22
	v_fmac_f32_e32 v122, v75, v23
	v_fmac_f32_e32 v122, v76, v24
	v_fmac_f32_e32 v122, v77, v25
	v_fmac_f32_e32 v122, v78, v26
	v_fmac_f32_e32 v122, v79, v27
	v_fmac_f32_e32 v122, v80, v28
	v_fmac_f32_e32 v122, v81, v29
	v_fmac_f32_e32 v122, v82, v30
	v_fmac_f32_e32 v122, v83, v31
	v_fmac_f32_e32 v122, v84, v32
	v_fmac_f32_e32 v122, v85, v33
	v_fmac_f32_e32 v122, v86, v34
	v_fmac_f32_e32 v122, v87, v35
	v_mul_f32_e32 v123, v88, v20
	v_fmac_f32_e32 v123, v89, v21
	v_fmac_f32_e32 v123, v90, v22
	v_fmac_f32_e32 v123, v91, v23
	v_fmac_f32_e32 v123, v92, v24
	v_fmac_f32_e32 v123, v93, v25
	v_fmac_f32_e32 v123, v94, v26
	v_fmac_f32_e32 v123, v95, v27
	v_fmac_f32_e32 v123, v96, v28
	v_fmac_f32_e32 v123, v97, v29
	v_fmac_f32_e32 v123, v98, v30
	v_fmac_f32_e32 v123, v99, v31
	v_fmac_f32_e32 v123, v100, v32
	v_fmac_f32_e32 v123, v101, v33
	v_fmac_f32_e32 v123, v102, v34
	v_fmac_f32_e32 v123, v103, v35
	v_mul_f32_e32 v124, v104, v20
	v_fmac_f32_e32 v124, v105, v21
	v_fmac_f32_e32 v124, v106, v22
	v_fmac_f32_e32 v124, v107, v23
	v_fmac_f32_e32 v124, v108, v24
	v_fmac_f32_e32 v124, v109, v25
	v_fmac_f32_e32 v124, v110, v26
	v_fmac_f32_e32 v124, v111, v27
	v_fmac_f32_e32 v124, v112, v28
	v_fmac_f32_e32 v124, v113, v29
	v_fmac_f32_e32 v124, v114, v30
	v_fmac_f32_e32 v124, v115, v31
	v_fmac_f32_e32 v124, v116, v32
	v_fmac_f32_e32 v124, v117, v33
	v_fmac_f32_e32 v124, v118, v34
	v_fmac_f32_e32 v124, v119, v35
	s_nop 1
	v_add_f32_dpp v120, v120, v120 quad_perm:[1,0,3,2] row_mask:0xf bank_mask:0xf bound_ctrl:1
	v_add_f32_dpp v121, v121, v121 quad_perm:[1,0,3,2] row_mask:0xf bank_mask:0xf bound_ctrl:1
	v_add_f32_dpp v122, v122, v122 quad_perm:[1,0,3,2] row_mask:0xf bank_mask:0xf bound_ctrl:1
	v_add_f32_dpp v123, v123, v123 quad_perm:[1,0,3,2] row_mask:0xf bank_mask:0xf bound_ctrl:1
	v_add_f32_dpp v124, v124, v124 quad_perm:[1,0,3,2] row_mask:0xf bank_mask:0xf bound_ctrl:1
	s_nop 1
	v_add_f32_dpp v120, v120, v120 quad_perm:[2,3,0,1] row_mask:0xf bank_mask:0xf bound_ctrl:1
	v_add_f32_dpp v121, v121, v121 quad_perm:[2,3,0,1] row_mask:0xf bank_mask:0xf bound_ctrl:1
	v_add_f32_dpp v122, v122, v122 quad_perm:[2,3,0,1] row_mask:0xf bank_mask:0xf bound_ctrl:1
	v_add_f32_dpp v123, v123, v123 quad_perm:[2,3,0,1] row_mask:0xf bank_mask:0xf bound_ctrl:1
	v_add_f32_dpp v124, v124, v124 quad_perm:[2,3,0,1] row_mask:0xf bank_mask:0xf bound_ctrl:1
	s_nop 1
	v_add_f32_dpp v120, v120, v120 row_half_mirror row_mask:0xf bank_mask:0xf bound_ctrl:1
	v_add_f32_dpp v121, v121, v121 row_half_mirror row_mask:0xf bank_mask:0xf bound_ctrl:1
	v_add_f32_dpp v122, v122, v122 row_half_mirror row_mask:0xf bank_mask:0xf bound_ctrl:1
	v_add_f32_dpp v123, v123, v123 row_half_mirror row_mask:0xf bank_mask:0xf bound_ctrl:1
	v_add_f32_dpp v124, v124, v124 row_half_mirror row_mask:0xf bank_mask:0xf bound_ctrl:1
	s_nop 1
	v_add_f32_dpp v120, v120, v120 row_mirror row_mask:0xf bank_mask:0xf bound_ctrl:1
	v_add_f32_dpp v121, v121, v121 row_mirror row_mask:0xf bank_mask:0xf bound_ctrl:1
	v_add_f32_dpp v122, v122, v122 row_mirror row_mask:0xf bank_mask:0xf bound_ctrl:1
	v_add_f32_dpp v123, v123, v123 row_mirror row_mask:0xf bank_mask:0xf bound_ctrl:1
	v_add_f32_dpp v124, v124, v124 row_mirror row_mask:0xf bank_mask:0xf bound_ctrl:1
	s_nop 1
	v_readlane_b32 s66, v120, 0
	v_readlane_b32 s67, v120, 16
	v_readlane_b32 s14, v120, 32
	v_readlane_b32 s15, v120, 48
	s_nop 1
	v_mov_b32_e32 v125, s66
	v_add_f32_e32 v125, s67, v125
	v_add_f32_e32 v125, s14, v125
	v_add_f32_e32 v125, s15, v125
	v_readlane_b32 s66, v121, 0
	v_readlane_b32 s67, v121, 16
	v_readlane_b32 s14, v121, 32
	v_readlane_b32 s15, v121, 48
	s_nop 1
	v_mov_b32_e32 v126, s66
	v_add_f32_e32 v126, s67, v126
	v_add_f32_e32 v126, s14, v126
	v_add_f32_e32 v126, s15, v126
	v_readlane_b32 s66, v122, 0
	v_readlane_b32 s67, v122, 16
	v_readlane_b32 s14, v122, 32
	v_readlane_b32 s15, v122, 48
	s_nop 1
	v_mov_b32_e32 v127, s66
	v_add_f32_e32 v127, s67, v127
	v_add_f32_e32 v127, s14, v127
	v_add_f32_e32 v127, s15, v127
	v_readlane_b32 s66, v123, 0
	v_readlane_b32 s67, v123, 16
	v_readlane_b32 s14, v123, 32
	v_readlane_b32 s15, v123, 48
	s_nop 1
	v_mov_b32_e32 v128, s66
	v_add_f32_e32 v128, s67, v128
	v_add_f32_e32 v128, s14, v128
	v_add_f32_e32 v128, s15, v128
	v_readlane_b32 s66, v124, 0
	v_readlane_b32 s67, v124, 16
	v_readlane_b32 s14, v124, 32
	v_readlane_b32 s15, v124, 48
	s_nop 1
	v_mov_b32_e32 v129, s66
	v_add_f32_e32 v129, s67, v129
	v_add_f32_e32 v129, s14, v129
	v_add_f32_e32 v129, s15, v129
	s_mov_b64 exec, 1
	global_store_dword v1, v125, s[64:65]
	s_add_u32 s64, s64, 0x5800
	s_addc_u32 s65, s65, 0
	global_store_dword v1, v126, s[64:65]
	s_add_u32 s64, s64, 0x5800
	s_addc_u32 s65, s65, 0
	global_store_dword v1, v127, s[64:65]
	s_add_u32 s64, s64, 0x5800
	s_addc_u32 s65, s65, 0
	global_store_dword v1, v128, s[64:65]
	s_add_u32 s64, s64, 0x5800
	s_addc_u32 s65, s65, 0
	global_store_dword v1, v129, s[64:65]
	s_mov_b64 exec, -1
	s_addk_i32 s59, 0x600
	s_branch .Lb_loop

.LBB0_888:
	s_or_b64 exec, exec, s[2:3]
	s_movk_i32 s2, 0x2200
	v_cmp_gt_i32_e32 vcc, s2, v10
	s_and_saveexec_b64 s[2:3], vcc
	s_cbranch_execz .LBB0_905
	v_readlane_b32 s8, v224, 34
	v_readlane_b32 s9, v224, 35
	s_load_dwordx2 s[6:7], s[8:9], 0x1b0
	s_load_dwordx4 s[44:47], s[8:9], 0x210
	v_lshlrev_b32_e32 v0, 6, v23
	v_cmp_lt_i32_e32 vcc, v151, v152
	v_cmp_eq_u32_e64 s[40:41], 0, v23
	s_waitcnt lgkmcnt(0)
	v_lshl_add_u64 v[12:13], s[6:7], 0, v[0:1]
	v_cndmask_b32_e32 v0, v150, v151, vcc
	v_cmp_lt_i32_e32 vcc, v153, v152
	v_lshlrev_b32_e32 v11, 2, v0
	s_mov_b64 s[6:7], 0
	v_cndmask_b32_e32 v0, v150, v153, vcc
	v_lshlrev_b32_e32 v22, 2, v0
	v_lshlrev_b32_e32 v0, 1, v2
	s_branch .LBB0_891
.LBB0_890:
	s_or_b64 exec, exec, s[8:9]
	v_readlane_b32 s8, v224, 14
	v_readlane_b32 s9, v224, 15
	s_nop 0
	v_add_u32_e32 v10, s8, v10
	s_movk_i32 s8, 0x21ff
	v_cmp_lt_i32_e32 vcc, s8, v10
	s_or_b64 s[6:7], vcc, s[6:7]
	s_andn2_b64 exec, exec, s[6:7]
	s_cbranch_execz .LBB0_905
.LBB0_891:
	s_mov_b32 s8, 0x78787879
	v_mul_hi_i32 v2, v10, s8
	s_waitcnt lgkmcnt(0)
	v_lshrrev_b32_e32 v3, 31, v2
	v_ashrrev_i32_e32 v2, 10, v2
	v_add_u32_e32 v25, v2, v3
	s_movk_i32 s8, 0xf780
	v_mad_i32_i24 v4, v25, s8, v10
	s_movk_i32 s8, 0x87f
	v_cmp_lt_i32_e32 vcc, s8, v4
	s_movk_i32 s8, 0x880
	v_cmp_gt_i32_e64 s[42:43], s8, v4
	v_mov_b64_e32 v[16:17], s[46:47]
	s_and_saveexec_b64 s[8:9], s[42:43]
	s_xor_b64 s[8:9], exec, s[8:9]
	s_cbranch_execz .LBB0_893
	v_readlane_b32 s12, v224, 34
	v_readlane_b32 s13, v224, 35
	s_load_dwordx2 s[12:13], s[12:13], 0x100
	v_mul_i32_i24_e32 v2, 0x880, v25
	v_ashrrev_i32_e32 v3, 31, v2
	v_lshlrev_b64 v[2:3], 11, v[2:3]
	v_mov_b64_e32 v[16:17], s[44:45]
	s_waitcnt lgkmcnt(0)
	v_lshl_add_u64 v[2:3], s[12:13], 0, v[2:3]
